# expert-weight phase: the eight partial-dot slice loads issued together with counted waits
# speedup vs baseline: 1.0029x; 1.0029x over previous
; DI void phase_peer_w(int nrows, int wv) {
;     ...
;     for (int i = blockIdx.x * NTHREADS + F.tid; i < n4; i += F.G * NTHREADS) {
;         const u32x2 ep = *(const u32x2*)(RI + (size_t)i * 4); const u32x4 e = {ep.x & 0xffffu, ep.x >> 16, ep.y & 0xffffu, ep.y >> 16}; const f32x4 gt = *(const f32x4*)(RG + (size_t)i * 4);
;         f32x4 sum = *(const f32x4*)(P + (size_t)i * 4);
; #pragma unroll
;         for (int xx = 1; xx < 8; ++xx) sum += *(const f32x4*)(P + (size_t)xx * NTOK * 128 + (size_t)i * 4);
;         f32x4 w;
;         w.x = gt.x * SV[e.x] * gelu_fast(SU[e.x] * sum.x); w.y = gt.y * SV[e.y] * gelu_fast(SU[e.y] * sum.y); w.z = gt.z * SV[e.z] * gelu_fast(SU[e.z] * sum.z); w.w = gt.w * SV[e.w] * gelu_fast(SU[e.w] * sum.w);
;         *(f32x4*)(W + (size_t)i * 4) = w;
;     }
.LBB0_1037:
	v_lshl_add_u64 v[0:1], s[6:7], 0, v[8:9]
	v_lshl_add_u64 v[10:11], s[6:7], 0, v[6:7]
	global_load_dwordx2 v[12:13], v[0:1], off
	v_add_co_u32_e32 v0, vcc, 0x43500000, v10
	s_nop 1
	v_addc_co_u32_e32 v1, vcc, 0, v11, vcc
	global_load_dwordx4 v[0:3], v[0:1], off
	v_add_co_u32_e32 v22, vcc, 0x39c00000, v10
	s_nop 1
	v_addc_co_u32_e32 v23, vcc, 0, v11, vcc
	global_load_dwordx4 v[14:17], v[22:23], off
	v_add_co_u32_e32 v22, vcc, 0x3a500000, v10
	s_nop 1
	v_addc_co_u32_e32 v23, vcc, 0, v11, vcc
	global_load_dwordx4 v[18:21], v[22:23], off
	v_add_co_u32_e32 v22, vcc, 0x3ae00000, v10
	s_nop 1
	v_addc_co_u32_e32 v23, vcc, 0, v11, vcc
	global_load_dwordx4 v[30:33], v[22:23], off
	v_add_co_u32_e32 v22, vcc, 0x3b700000, v10
	s_nop 1
	v_addc_co_u32_e32 v23, vcc, 0, v11, vcc
	global_load_dwordx4 v[34:37], v[22:23], off
	v_add_co_u32_e32 v22, vcc, 0x3c000000, v10
	s_nop 1
	v_addc_co_u32_e32 v23, vcc, 0, v11, vcc
	global_load_dwordx4 v[38:41], v[22:23], off
	v_add_co_u32_e32 v22, vcc, 0x3c900000, v10
	s_nop 1
	v_addc_co_u32_e32 v23, vcc, 0, v11, vcc
	global_load_dwordx4 v[42:45], v[22:23], off
	v_add_co_u32_e32 v22, vcc, 0x3d200000, v10
	s_nop 1
	v_addc_co_u32_e32 v23, vcc, 0, v11, vcc
	global_load_dwordx4 v[46:49], v[22:23], off
	v_add_co_u32_e32 v22, vcc, 0x3db00000, v10
	s_nop 1
	v_addc_co_u32_e32 v23, vcc, 0, v11, vcc
	global_load_dwordx4 v[50:53], v[22:23], off
	v_add_u32_e32 v4, s14, v4
	v_lshl_add_u64 v[6:7], v[6:7], 0, s[16:17]
	v_lshl_add_u64 v[8:9], v[8:9], 0, s[18:19]
	s_mov_b32 s0, 0xbf3a00e3
	v_mov_b64_e32 v[24:25], s[0:1]
	s_waitcnt vmcnt(9)
	v_lshlrev_b32_sdwa v5, v249, v12 dst_sel:DWORD dst_unused:UNUSED_PAD src0_sel:DWORD src1_sel:WORD_0
	s_waitcnt vmcnt(6)
	v_pk_add_f32 v[18:19], v[14:15], v[18:19]
	v_pk_add_f32 v[20:21], v[16:17], v[20:21]
	s_waitcnt vmcnt(5)
	v_pk_add_f32 v[18:19], v[18:19], v[30:31]
	v_pk_add_f32 v[20:21], v[20:21], v[32:33]
	s_waitcnt vmcnt(4)
	v_pk_add_f32 v[18:19], v[18:19], v[34:35]
	v_pk_add_f32 v[20:21], v[20:21], v[36:37]
	s_waitcnt vmcnt(3)
	v_pk_add_f32 v[18:19], v[18:19], v[38:39]
	v_pk_add_f32 v[20:21], v[20:21], v[40:41]
	s_waitcnt vmcnt(2)
	v_pk_add_f32 v[18:19], v[18:19], v[42:43]
	v_pk_add_f32 v[20:21], v[20:21], v[44:45]
	s_waitcnt vmcnt(1)
	v_pk_add_f32 v[18:19], v[18:19], v[46:47]
	v_pk_add_f32 v[20:21], v[20:21], v[48:49]
	s_waitcnt vmcnt(0)
	v_pk_add_f32 v[16:17], v[20:21], v[52:53]
	v_pk_add_f32 v[14:15], v[18:19], v[50:51]
	global_load_dword v18, v5, s[12:13]
	global_load_dword v20, v5, s[10:11]
	v_lshlrev_b32_sdwa v5, v249, v12 dst_sel:DWORD dst_unused:UNUSED_PAD src0_sel:DWORD src1_sel:WORD_1
	global_load_dword v19, v5, s[12:13]
	global_load_dword v21, v5, s[10:11]
	s_waitcnt vmcnt(1)
	v_pk_mul_f32 v[0:1], v[0:1], v[18:19]
	s_waitcnt vmcnt(0)
	v_pk_mul_f32 v[14:15], v[14:15], v[20:21]
	s_nop 0
	v_fma_f32 v5, |v14|, s23, 1.0
	v_pk_mul_f32 v[22:23], v[14:15], v[14:15]
	v_rcp_f32_e32 v20, v5
	v_mul_f32_e32 v5, 0xbf38aa3b, v22
	v_exp_f32_e32 v22, v5
	v_fma_f32 v5, |v15|, s23, 1.0
	v_rcp_f32_e32 v21, v5
	v_mul_f32_e32 v5, 0xbf38aa3b, v23
	v_exp_f32_e32 v23, v5
	v_lshlrev_b32_sdwa v5, v249, v13 dst_sel:DWORD dst_unused:UNUSED_PAD src0_sel:DWORD src1_sel:WORD_0
	v_pk_fma_f32 v[26:27], v[20:21], s[26:27], v[24:25] op_sel_hi:[1,0,0]
	v_cmp_gt_f32_e64 s[2:3], 0, v14
	v_pk_fma_f32 v[26:27], v[20:21], v[26:27], s[28:29] op_sel_hi:[1,1,0]
	v_cmp_gt_f32_e64 s[4:5], 0, v15
	v_pk_fma_f32 v[26:27], v[20:21], v[26:27], s[30:31] op_sel_hi:[1,1,0]
	s_nop 0
	v_pk_fma_f32 v[26:27], v[20:21], v[26:27], s[34:35] op_sel_hi:[1,1,0]
	s_nop 0
	v_pk_mul_f32 v[20:21], v[20:21], v[26:27]
	global_load_dword v12, v5, s[12:13]
	global_load_dword v26, v5, s[10:11]
	v_lshlrev_b32_sdwa v5, v249, v13 dst_sel:DWORD dst_unused:UNUSED_PAD src0_sel:DWORD src1_sel:WORD_1
	global_load_dword v13, v5, s[12:13]
	global_load_dword v27, v5, s[10:11]
	v_pk_mul_f32 v[20:21], v[22:23], v[20:21]
	s_waitcnt vmcnt(1)
	v_pk_mul_f32 v[2:3], v[2:3], v[12:13]
	s_waitcnt vmcnt(0)
	v_pk_mul_f32 v[16:17], v[16:17], v[26:27]
	v_pk_mul_f32 v[22:23], v[14:15], v[20:21]
	v_fma_f32 v5, |v16|, s23, 1.0
	v_pk_mul_f32 v[28:29], v[16:17], v[16:17]
	v_rcp_f32_e32 v26, v5
	v_mul_f32_e32 v5, 0xbf38aa3b, v28
	v_exp_f32_e32 v28, v5
	v_fma_f32 v5, |v17|, s23, 1.0
	v_rcp_f32_e32 v27, v5
	v_mul_f32_e32 v5, 0xbf38aa3b, v29
	v_exp_f32_e32 v29, v5
	v_cmp_gt_f32_e32 vcc, 0, v16
	v_pk_fma_f32 v[24:25], v[26:27], s[26:27], v[24:25] op_sel_hi:[1,0,0]
	v_pk_fma_f32 v[12:13], v[14:15], v[20:21], v[14:15] neg_lo:[1,0,0] neg_hi:[1,0,0]
	v_pk_fma_f32 v[24:25], v[26:27], v[24:25], s[28:29] op_sel_hi:[1,1,0]
	v_cmp_gt_f32_e64 s[0:1], 0, v17
	v_pk_fma_f32 v[24:25], v[26:27], v[24:25], s[30:31] op_sel_hi:[1,1,0]
	v_cndmask_b32_e64 v13, v13, v23, s[4:5]
	v_pk_fma_f32 v[24:25], v[26:27], v[24:25], s[34:35] op_sel_hi:[1,1,0]
	v_cndmask_b32_e64 v12, v12, v22, s[2:3]
	v_pk_mul_f32 v[24:25], v[26:27], v[24:25]
	v_pk_mul_f32 v[0:1], v[0:1], v[12:13]
	v_pk_mul_f32 v[24:25], v[28:29], v[24:25]
	s_nop 0
	v_pk_mul_f32 v[26:27], v[16:17], v[24:25]
	v_pk_fma_f32 v[14:15], v[16:17], v[24:25], v[16:17] neg_lo:[1,0,0] neg_hi:[1,0,0]
	s_nop 0
	v_cndmask_b32_e32 v14, v14, v26, vcc
	v_add_co_u32_e32 v10, vcc, 0x3e400000, v10
	v_cndmask_b32_e64 v15, v15, v27, s[0:1]
	s_nop 0
	v_addc_co_u32_e32 v11, vcc, 0, v11, vcc
	v_cmp_le_i32_e32 vcc, s22, v4
	v_pk_mul_f32 v[2:3], v[2:3], v[14:15]
	s_or_b64 s[20:21], vcc, s[20:21]
	global_store_dwordx4 v[10:11], v[0:3], off
	s_andn2_b64 exec, exec, s[20:21]
	s_cbranch_execnz .LBB0_1037
